# stick-breaking units: per-workgroup LDS work queue (waves pull the workgroup's own units) instead of fixed 2-3 units per wave
# baseline (speedup 1.0000x reference)
; #define LAS __attribute__((address_space(3)))
; __device__ __forceinline__ void sb_queue(const Args& a, int l, unsigned* qc, unsigned lo, unsigned hi_, LAS unsigned char* wl, int lane) {
;     const int wv = __builtin_amdgcn_readfirstlane((int)(threadIdx.x >> 6));
;     const unsigned v = (blockIdx.x + 224u) & 255u;
;     for (int k = 0; k < 3; ++k) {
;         int u; unsigned p = 0u; bool slow = false;
;         if (k == 0) { if (wv == 0 && v < 128u) slow = true; else p = 2048u + v * 8u + (unsigned)wv; }
;         else if (k == 1) p = v * 8u + (unsigned)wv;
;         else { if (wv != 4 || v >= 128u) break; p = 2048u + v * 8u; }
;         if (slow) u = 4096 + (int)v;
;         else if (p < 3904u) u = (int)(p / 122u) * 128 + 6 + (int)(p % 122u);
;         else { const unsigned x = p - 3904u; u = (int)(x / 6u) * 128 + (int)(x % 6u); }
;         sb_unit(a, l, u, wl, lane);
;     }
.LBB0_859:
	s_mov_b64 exec, 1
	v_mov_b32_e32 v0, 0x20020
	v_mov_b32_e32 v2, 1
	ds_add_rtn_u32 v0, v0, v2
	s_mov_b64 exec, -1
	v_readlane_b32 s8, v247, 6
	v_readlane_b32 s9, v247, 7
	v_readlane_b32 s6, v247, 8
	s_waitcnt lgkmcnt(0)
	v_readfirstlane_b32 s19, v0
	s_mov_b64 s[16:17], -1
	s_nop 1
	s_and_b64 vcc, exec, s[8:9]
	s_cbranch_vccz .Lq_nonslow
	s_cmp_eq_u32 s19, 0
	s_cbranch_scc1 .Lq_slow
	s_add_i32 s19, s19, -1
.Lq_nonslow:
	s_cmp_gt_u32 s19, 15
	s_cbranch_scc1 .Lq_done
	s_cmp_lt_u32 s19, 8
	s_cselect_b32 s7, s30, s6
	s_and_b32 s19, s19, 7
	s_add_i32 s19, s19, s7

; __device__ __forceinline__ void sb_unit(const Args& a, int l, int u, LAS unsigned char* wl, int lane) {
;     ...
;     if (u < 4096) { const int b = u >> 10, qb = u & 127; h = (u >> 7) & 7; qrow0 = b * 4096 + 32 * qb; q0pos = 32 * qb; kbrow0 = b * 4096; }
;     else { const int u2 = u - 4096, b = u2 >> 4, qb = u2 & 1; h = (u2 >> 1) & 7; qrow0 = MP + b * 64 + 32 * qb; q0pos = 1024 + 32 * qb; kbrow0 = MP + b * 64 - 1024; ncache = 16;
;         kc = a.in[2] + ((size_t)(l * 8 + b) * 1024) * 512 + h * 64; vc = a.in[3] + ((size_t)(l * 8 + b) * 1024) * 512 + h * 64; }
.Lq_slow:
	s_mov_b32 s18, s31
	s_mov_b64 s[6:7], -1
	s_branch .LBB0_872
.Lq_done:
	s_mov_b64 s[6:7], -1
	s_branch .LBB0_858
.LBB0_872:
	s_cmpk_gt_u32 s18, 0xfff
	s_mov_b64 s[16:17], -1
	s_cbranch_scc0 .LBB0_874
	s_add_i32 s6, s18, 0xfffff000
	s_lshr_b32 s6, s6, 4
	s_lshl_b32 s8, s18, 5
	s_lshl_b32 s7, s6, 6
	s_and_b32 s9, s8, 32
	s_or_b32 s16, s7, s9
	s_add_i32 s82, s6, s26
	v_readlane_b32 s52, v249, 0
	s_add_i32 s28, s16, 0x4000
	s_or_b32 s20, s9, 0x400
	s_add_i32 s19, s7, 0x3c00
	s_lshl_b64 s[6:7], s[82:83], 21
	v_readlane_b32 s56, v249, 4
	v_readlane_b32 s57, v249, 5
	s_add_u32 s9, s56, s6
	s_addc_u32 s16, s57, s7
	s_and_b32 s82, s8, 0x1c0
	s_lshl_b32 s17, s82, 2
	s_add_u32 s8, s9, s17
	v_readlane_b32 s58, v249, 6
	s_addc_u32 s9, s16, 0
	v_readlane_b32 s59, v249, 7
	s_add_u32 s6, s58, s6
	s_addc_u32 s7, s59, s7
	s_add_u32 s6, s6, s17
	s_addc_u32 s7, s7, 0
	s_mov_b64 s[16:17], 0
	v_readlane_b32 s53, v249, 1
	v_readlane_b32 s54, v249, 2
	v_readlane_b32 s55, v249, 3
	v_readlane_b32 s60, v249, 8
	v_readlane_b32 s61, v249, 9
	v_readlane_b32 s62, v249, 10
	v_readlane_b32 s63, v249, 11
	v_readlane_b32 s64, v249, 12
	v_readlane_b32 s65, v249, 13
	v_readlane_b32 s66, v249, 14
	v_readlane_b32 s67, v249, 15

; #define LAS __attribute__((address_space(3)))
; __device__ __forceinline__ unsigned f2bf(float f) { unsigned u = __builtin_bit_cast(unsigned, f); return (u + 0x7fffu + ((u >> 16) & 1u)) >> 16; }
; __device__ __forceinline__ int crow(int r, int hi) { return (r & 3) + 8 * (r >> 2) + 4 * hi; }
; __device__ __forceinline__ void sb_unit(const Args& a, int l, int u, LAS unsigned char* wl, int lane) {
;     ...
;         if (__builtin_amdgcn_ballot_w64(carry >= 1e-37f) == 0ull) break;
;     }
;     ...
;     LAS bf16_t* stg = (LAS bf16_t*)wl;
; #pragma unroll
;     for (int r = 0; r < 16; ++r) { const int orow = crow(r, hi);
; #pragma unroll
;         for (int d0 = 0; d0 < 2; ++d0) stg[orow * 64 + d0 * 32 + r32] = (bf16_t)f2bf(o[d0][r]); }
;     asm volatile("s_waitcnt lgkmcnt(0)" ::: "memory");
; #pragma unroll
;     for (int i = 0; i < 4; ++i) { const int row = i * 8 + (lane >> 3), ch = lane & 7; const u32x4 v = *(const LAS u32x4*)(stg + row * 64 + ch * 8);
;         *(u32x4*)(MIX + (size_t)(qrow0 + row) * D + 512 + h * 64 + ch * 8) = v; }
.LBB0_898:
	v_mul_f32_e32 v2, v6, v7
	v_mul_f32_e32 v189, v2, v0
	s_mov_b32 s6, 0x2081cea
	v_cmp_le_f32_e32 vcc, s6, v189
	s_cmp_lg_u64 vcc, 0
	s_cselect_b64 s[8:9], -1, 0
	s_add_i32 s6, s18, -1
	s_cmp_gt_i32 s18, 0
	s_waitcnt lgkmcnt(0)
	s_cselect_b64 s[22:23], -1, 0
	s_and_b64 s[8:9], s[22:23], s[8:9]
	s_sub_i32 s19, s19, 64
	s_and_b64 vcc, exec, s[8:9]
	s_cbranch_vccnz .LBB0_879
	v_bfe_u32 v0, v32, 16, 1
	v_add3_u32 v0, v32, v0, s2
	ds_write_b16_d16_hi v209, v0
	v_bfe_u32 v0, v16, 16, 1
	v_add3_u32 v0, v16, v0, s2
	ds_write_b16_d16_hi v209, v0 offset:64
	v_bfe_u32 v0, v33, 16, 1
	v_add3_u32 v0, v33, v0, s2
	ds_write_b16_d16_hi v209, v0 offset:128
	v_bfe_u32 v0, v17, 16, 1
	v_add3_u32 v0, v17, v0, s2
	ds_write_b16_d16_hi v209, v0 offset:192
	v_bfe_u32 v0, v34, 16, 1
	v_add3_u32 v0, v34, v0, s2
	ds_write_b16_d16_hi v209, v0 offset:256
	v_bfe_u32 v0, v18, 16, 1
	v_add3_u32 v0, v18, v0, s2
	ds_write_b16_d16_hi v209, v0 offset:320
	v_bfe_u32 v0, v35, 16, 1
	v_add3_u32 v0, v35, v0, s2
	ds_write_b16_d16_hi v209, v0 offset:384
	v_bfe_u32 v0, v19, 16, 1
	v_add3_u32 v0, v19, v0, s2
	ds_write_b16_d16_hi v209, v0 offset:448
	v_bfe_u32 v0, v36, 16, 1
	v_add3_u32 v0, v36, v0, s2
	ds_write_b16_d16_hi v209, v0 offset:1024
	v_bfe_u32 v0, v20, 16, 1
	v_add3_u32 v0, v20, v0, s2
	ds_write_b16_d16_hi v209, v0 offset:1088
	v_bfe_u32 v0, v37, 16, 1
	v_add3_u32 v0, v37, v0, s2
	ds_write_b16_d16_hi v209, v0 offset:1152
	v_bfe_u32 v0, v21, 16, 1
	v_add3_u32 v0, v21, v0, s2
	ds_write_b16_d16_hi v209, v0 offset:1216
	v_bfe_u32 v0, v38, 16, 1
	v_add3_u32 v0, v38, v0, s2
	ds_write_b16_d16_hi v209, v0 offset:1280
	v_bfe_u32 v0, v22, 16, 1
	v_add3_u32 v0, v22, v0, s2
	ds_write_b16_d16_hi v209, v0 offset:1344
	v_bfe_u32 v0, v39, 16, 1
	v_add3_u32 v0, v39, v0, s2
	ds_write_b16_d16_hi v209, v0 offset:1408
	v_bfe_u32 v0, v23, 16, 1
	v_add3_u32 v0, v23, v0, s2
	ds_write_b16_d16_hi v209, v0 offset:1472
	v_bfe_u32 v0, v40, 16, 1
	v_add3_u32 v0, v40, v0, s2
	ds_write_b16_d16_hi v209, v0 offset:2048
	v_bfe_u32 v0, v24, 16, 1
	v_add3_u32 v0, v24, v0, s2
	ds_write_b16_d16_hi v209, v0 offset:2112
	v_bfe_u32 v0, v41, 16, 1
	v_add3_u32 v0, v41, v0, s2
	ds_write_b16_d16_hi v209, v0 offset:2176
	v_bfe_u32 v0, v25, 16, 1
	v_add3_u32 v0, v25, v0, s2
	ds_write_b16_d16_hi v209, v0 offset:2240
	v_bfe_u32 v0, v42, 16, 1
	v_add3_u32 v0, v42, v0, s2
	ds_write_b16_d16_hi v209, v0 offset:2304
	v_bfe_u32 v0, v26, 16, 1
	v_add3_u32 v0, v26, v0, s2
	ds_write_b16_d16_hi v209, v0 offset:2368
	v_bfe_u32 v0, v43, 16, 1
	v_add3_u32 v0, v43, v0, s2
	ds_write_b16_d16_hi v209, v0 offset:2432
	v_bfe_u32 v0, v27, 16, 1
	v_add3_u32 v0, v27, v0, s2
	ds_write_b16_d16_hi v209, v0 offset:2496
	v_bfe_u32 v0, v44, 16, 1
	v_add3_u32 v0, v44, v0, s2
	ds_write_b16_d16_hi v209, v0 offset:3072
	v_bfe_u32 v0, v28, 16, 1
	v_add3_u32 v0, v28, v0, s2
	ds_write_b16_d16_hi v209, v0 offset:3136
	v_bfe_u32 v0, v45, 16, 1
	v_add3_u32 v0, v45, v0, s2
	ds_write_b16_d16_hi v209, v0 offset:3200
	v_bfe_u32 v0, v29, 16, 1
	v_add3_u32 v0, v29, v0, s2
	ds_write_b16_d16_hi v209, v0 offset:3264
	v_bfe_u32 v0, v46, 16, 1
	v_add3_u32 v0, v46, v0, s2
	ds_write_b16_d16_hi v209, v0 offset:3328
	v_bfe_u32 v0, v30, 16, 1
	v_add3_u32 v0, v30, v0, s2
	ds_write_b16_d16_hi v209, v0 offset:3392
	v_bfe_u32 v0, v47, 16, 1
	v_add3_u32 v0, v47, v0, s2
	ds_write_b16_d16_hi v209, v0 offset:3456
	v_bfe_u32 v0, v31, 16, 1
	v_add3_u32 v0, v31, v0, s2
	ds_write_b16_d16_hi v209, v0 offset:3520
	v_add_u32_e32 v0, s28, v197
	s_waitcnt lgkmcnt(0)
	v_lshlrev_b64 v[6:7], 11, v[0:1]
	ds_read_b128 v[2:5], v210
	v_lshl_add_u64 v[6:7], s[90:91], 0, v[6:7]
	v_lshl_add_u64 v[6:7], v[6:7], 0, s[16:17]
	v_mov_b32_e32 v177, v1
	v_lshl_add_u64 v[6:7], v[6:7], 0, v[176:177]
	s_mov_b32 s6, 0x5900000
	v_add_co_u32_e32 v10, vcc, s6, v6
	v_add_u32_e32 v0, s28, v198
	s_nop 0
	v_addc_co_u32_e32 v11, vcc, 0, v7, vcc
	ds_read_b128 v[6:9], v211
	s_waitcnt lgkmcnt(1)
	global_store_dwordx4 v[10:11], v[2:5], off offset:1024
	s_add_i32 s27, s27, 1
	s_cmp_eq_u32 s27, 3
	v_lshlrev_b64 v[2:3], 11, v[0:1]
	v_lshl_add_u64 v[2:3], s[90:91], 0, v[2:3]
	v_lshl_add_u64 v[2:3], v[2:3], 0, s[16:17]
	v_lshl_add_u64 v[2:3], v[2:3], 0, v[176:177]
	v_add_co_u32_e32 v2, vcc, s6, v2
	v_add_u32_e32 v0, s28, v199
	s_nop 0
	v_addc_co_u32_e32 v3, vcc, 0, v3, vcc
	s_waitcnt lgkmcnt(0)
	global_store_dwordx4 v[2:3], v[6:9], off offset:1024
	ds_read_b128 v[2:5], v212
	s_nop 0
	v_lshlrev_b64 v[6:7], 11, v[0:1]
	v_lshl_add_u64 v[6:7], s[90:91], 0, v[6:7]
	v_lshl_add_u64 v[6:7], v[6:7], 0, s[16:17]
	v_lshl_add_u64 v[6:7], v[6:7], 0, v[176:177]
	v_add_co_u32_e32 v10, vcc, s6, v6
	v_add_u32_e32 v0, s28, v207
	s_nop 0
	v_addc_co_u32_e32 v11, vcc, 0, v7, vcc
	ds_read_b128 v[6:9], v213
	s_waitcnt lgkmcnt(1)
	global_store_dwordx4 v[10:11], v[2:5], off offset:1024
	s_mov_b64 s[6:7], 0
	s_nop 0
	v_lshlrev_b64 v[2:3], 11, v[0:1]
	v_lshl_add_u64 v[2:3], s[90:91], 0, v[2:3]
	v_lshl_add_u64 v[2:3], v[2:3], 0, s[16:17]
	v_lshl_add_u64 v[2:3], v[2:3], 0, v[176:177]
	v_add_co_u32_e32 v2, vcc, 0x5900000, v2
	s_nop 1
	v_addc_co_u32_e32 v3, vcc, 0, v3, vcc
	s_waitcnt lgkmcnt(0)
	global_store_dwordx4 v[2:3], v[6:9], off offset:1024
	s_waitcnt lgkmcnt(0)
	s_branch .LBB0_858
; __device__ __forceinline__ void gla_vt(const u32x4 v0, const u32x4 v1, LAS unsigned char* L, int tid) {
;     LAS bf16_t* VT = (LAS bf16_t*)(L + GL_VT);
;     const int s = tid >> 3, dg = tid & 7;
;     const int sx = s ^ (8 * dg);
; #pragma unroll
;     for (int i = 0; i < 4; ++i) { VT[(16 * dg + 2 * i) * 72 + sx] = (bf16_t)(v0[i] & 0xffffu); VT[(16 * dg + 2 * i + 1) * 72 + sx] = (bf16_t)(v0[i] >> 16);
;         VT[(16 * dg + 8 + 2 * i) * 72 + sx] = (bf16_t)(v1[i] & 0xffffu); VT[(16 * dg + 8 + 2 * i + 1) * 72 + sx] = (bf16_t)(v1[i] >> 16); }
; }
; __device__ __forceinline__ void gla_a_item(const Args& a, int l, int item, LAS unsigned char* L, int tid, int wave, int lane) {
;     const int ch = item >> 2, h = item & 3, row0 = ch * 64;
;     const u32x4 kr = *(const u32x4*)((const bf16_t*)(a.ws + WS_GK) + (size_t)(row0 + (tid >> 3)) * 256 + h * 64 + 8 * (tid & 7));
;     const bf16_t* vp_ = (const bf16_t*)(a.ws + WS_GV) + (size_t)(row0 + (tid >> 3)) * 512 + h * 128 + 16 * (tid & 7);
;     const u32x4 pv0 = *(const u32x4*)vp_, pv1 = *(const u32x4*)(vp_ + 8);
;     gla_b(a, l, row0, h, L, tid);
;     LAS float* Bm = (LAS float*)(L + GL_BM); LAS bf16_t* KDT = (LAS bf16_t*)(L + GL_KDT); LAS bf16_t* VT = (LAS bf16_t*)(L + GL_VT);
;     { float* bg = a.out + O_Y + (size_t)item * 4096 + tid * 8; *(f32x4*)bg = *(const LAS f32x4*)(Bm + tid * 8); *(f32x4*)(bg + 4) = *(const LAS f32x4*)(Bm + tid * 8 + 4); }
;     {
;         const int s = tid >> 3, dg = tid & 7;
; #pragma unroll
;         for (int i = 0; i < 4; ++i) { const int d = 8 * dg + 2 * i;
;             KDT[d * 72 + (s ^ (8 * dg))] = (bf16_t)f2bf(bflo(kr[i]) * __expf(Bm[63 * 64 + d] - Bm[s * 64 + d]));
;             KDT[(d + 1) * 72 + (s ^ (8 * dg))] = (bf16_t)f2bf(bfhi(kr[i]) * __expf(Bm[63 * 64 + d + 1] - Bm[s * 64 + d + 1])); }
;     }
;     gla_vt(pv0, pv1, L, tid);
;     lds_barrier();
;     {
;         const int r32 = lane & 31, hi = lane >> 5, di = wave >> 2, vi = wave & 3;
;         f32x16 acc;
; #pragma unroll
;         for (int i = 0; i < 16; ++i) acc[i] = 0.f;
; #pragma unroll
;         for (int ks = 0; ks < 4; ++ks) { const int krow = 32 * di + r32, vrow = 32 * vi + r32;
; __global__ void __launch_bounds__(512, 2) fwd_kernel(Args a) {
;     ...
;         __syncthreads();
;         { FRESH(); for (int it = blockIdx.x; it < 1024; it += G) gla_a_item(a, l, it, L, tid, wave, lane); }
.LBB0_900:
	v_readlane_b32 s4, v247, 9
	v_readlane_b32 s5, v247, 10
	v_mov_b32_e32 v38, v200
	v_readlane_b32 s18, v246, 60
	v_cndmask_b32_e64 v0, 0, 1, s[4:5]
	v_readlane_b32 s26, v247, 11
	v_readlane_b32 s28, v247, 13
	v_readlane_b32 s30, v247, 15
	v_readlane_b32 s20, v246, 45
	s_barrier
	v_mov_b32_e32 v2, 0x20020
	v_mov_b32_e32 v3, 0
	ds_write_b32 v2, v3
	v_cmp_ne_u32_e64 s[78:79], 1, v0
	s_andn2_b64 vcc, exec, s[4:5]
	v_readfirstlane_b32 s4, v38
	v_readlane_b32 s19, v246, 61
	v_readlane_b32 s27, v247, 12
	v_readlane_b32 s29, v247, 14
	v_readlane_b32 s31, v247, 16
	v_readlane_b32 s21, v246, 46
	s_movk_i32 s25, 0x1000
	s_movk_i32 s23, 0x2000
	s_mov_b32 s24, 0x20000
	s_cbranch_vccnz .LBB0_919
	v_and_b32_e32 v6, 7, v38
	v_and_b32_e32 v3, 63, v38
	v_ashrrev_i32_e32 v40, 3, v38
	v_lshlrev_b32_e32 v0, 3, v6
	v_lshl_add_u32 v39, v3, 2, 0
	v_lshl_or_b32 v41, s42, 12, v3
	v_lshl_or_b32 v42, s42, 8, v3
	v_xor_b32_e32 v3, v0, v40
	v_lshl_add_u32 v44, v6, 5, 0
	s_movk_i32 s5, 0x460
	v_mad_u32_u24 v7, v6, s5, v44
	v_lshlrev_b32_e32 v3, 1, v3
	v_or_b32_e32 v8, 2, v0
	s_movk_i32 s5, 0xfba0
	v_lshlrev_b32_e32 v2, 4, v6
	v_add_u32_e32 v46, v7, v3
	v_mad_i32_i24 v47, v6, s5, v7
	v_mul_u32_u24_e32 v7, 0x90, v8
	v_mul_u32_u24_e32 v6, 0x8e0, v6
	s_ashr_i32 s5, s4, 8
	s_lshr_b32 s4, s4, 1
	v_add3_u32 v48, 0, v7, v3
	v_add3_u32 v51, v47, v6, v3
	v_and_b32_e32 v3, 31, v38
	s_and_b32 s4, s4, 0x60
	v_bfe_u32 v6, v38, 5, 1
	v_lshl_or_b32 v7, s5, 5, v3
	v_or_b32_e32 v3, s4, v3
	s_movk_i32 s4, 0x90
	v_mul_lo_u32 v8, v7, s4
	v_lshlrev_b32_e32 v9, 3, v6
	v_add_u32_e32 v8, 0, v8
	v_lshrrev_b32_e32 v11, 1, v3
	v_bitop3_b32 v12, v7, v9, 56 bitop3:0x6c
	v_mad_u32_u24 v10, v3, s4, 0
	v_lshl_add_u32 v52, v12, 1, v8
	v_bitop3_b32 v12, v11, v9, 56 bitop3:0x6c
	v_lshl_add_u32 v53, v12, 1, v10
	v_or_b32_e32 v12, 16, v9
	v_lshlrev_b32_e32 v4, 3, v38
	v_bitop3_b32 v13, v7, v12, 56 bitop3:0x6c
	v_bitop3_b32 v12, v11, v12, 56 bitop3:0x6c
	v_readlane_b32 s6, v246, 39
	v_ashrrev_i32_e32 v5, 31, v4
	v_lshl_add_u32 v55, v12, 1, v10
	v_or_b32_e32 v12, 32, v9
	v_or_b32_e32 v9, 48, v9
	s_lshl_b32 s4, s5, 12
	v_lshlrev_b32_e32 v6, 9, v6
	v_readlane_b32 s7, v246, 40
	v_lshl_add_u32 v54, v13, 1, v8
	v_bitop3_b32 v13, v7, v12, 56 bitop3:0x6c
	v_bitop3_b32 v7, v7, v9, 56 bitop3:0x6c
	v_lshl_add_u64 v[32:33], v[4:5], 2, s[6:7]
	v_or3_b32 v4, s4, v6, v3
	v_bitop3_b32 v12, v11, v12, 56 bitop3:0x6c
	v_lshl_add_u32 v58, v7, 1, v8
	v_bitop3_b32 v7, v11, v9, 56 bitop3:0x6c
	v_readlane_b32 s5, v246, 35
	v_ashrrev_i32_e32 v5, 31, v4
	v_lshl_add_u32 v43, v38, 5, 0
	v_lshl_add_u32 v45, v40, 8, v44
	v_add_u32_e32 v49, 0x120, v48
	v_add_u32_e32 v50, 0x240, v48
	v_lshl_add_u32 v56, v13, 1, v8
	v_lshl_add_u32 v57, v12, 1, v10
	v_lshl_add_u32 v59, v7, 1, v10
	v_cmp_gt_i32_e32 vcc, 64, v38
	v_lshl_add_u32 v60, v38, 2, 0
	v_add_u32_e32 v30, s5, v38
	v_lshl_add_u64 v[34:35], v[4:5], 1, s[90:91]
	v_lshlrev_b32_e32 v0, 1, v0
	v_lshlrev_b32_e32 v36, 1, v2
	v_readlane_b32 s14, v247, 17
	s_mov_b32 s15, s72
	s_branch .LBB0_903
